# P3 gating deal 5/11 units (workgroups with two q-projection units take 5, the others 11)
# baseline (speedup 1.0000x reference)
; __device__ __forceinline__ float bf_lo(unsigned u) { return __uint_as_float(u << 16); }
; #define tid (otid())
; __global__ void __launch_bounds__(512, 2) mega_fwd(Args a) {
;     ...
;         const int r32 = lane & 31, hi = lane >> 5, iblk = wave >> 1, dblk = wave & 1;
;         const int jt = tid >> 2, qd = tid & 3;
;         u32x4 r0, r1; f32x4 lgv[4], lbv[4];
;         const int ustep = (G == 256) ? 1 : G;
;         const int jx = vcu & 31;
;         const int u0 = (G == 256) ? (256 * (vcu >> 5) + (jx < 16 ? 7 * jx : 112 + 9 * (jx - 16))) : vcu;
;         const int ucnt = (G == 256) ? (bx < 128 ? 7 : 9) : (vcu < 2048 ? (2047 - vcu) / G + 1 : 0);
;         if (ucnt > 0) { const bf16_t* vp = Z + ((size_t)(u0 >> 3) * 128 + jt) * NZ + 1024 + (u0 & 7) * 64 + 16 * qd; r0 = *(const u32x4*)vp; r1 = *(const u32x4*)(vp + 8);
; #pragma unroll
;             for (int e4 = 0; e4 < 4; ++e4) { lgv[e4] = *(const f32x4*)(KA->gm_ln_g + (u0 & 7) * 64 + 16 * qd + 4 * e4); lbv[e4] = *(const f32x4*)(KA->gm_ln_b + (u0 & 7) * 64 + 16 * qd + 4 * e4); } }
;         for (int ui = 0, u = u0; ui < ucnt; ++ui, u += ustep) {
;             const int blk = u >> 3, h = u & 7; const size_t t0 = (size_t)blk * 128;
;             {
;                 float xv[16];
;                 xv[0] = bf_lo(r0.x); xv[1] = bf_hi(r0.x); xv[2] = bf_lo(r0.y); xv[3] = bf_hi(r0.y); xv[4] = bf_lo(r0.z); xv[5] = bf_hi(r0.z); xv[6] = bf_lo(r0.w); xv[7] = bf_hi(r0.w);
;                 xv[8] = bf_lo(r1.x); xv[9] = bf_hi(r1.x); xv[10] = bf_lo(r1.y); xv[11] = bf_hi(r1.y); xv[12] = bf_lo(r1.z); xv[13] = bf_hi(r1.z); xv[14] = bf_lo(r1.w); xv[15] = bf_hi(r1.w);
;                 float sm = 0.f;
; #pragma unroll
;                 for (int e = 0; e < 16; ++e) sm += xv[e];
;                 sm += __shfl_xor(sm, 1); sm += __shfl_xor(sm, 2);
;                 const float mu = sm * (1.0f / 64.0f); float q = 0.f;
; #pragma unroll
;                 for (int e = 0; e < 16; ++e) { xv[e] -= mu; q += xv[e] * xv[e]; }
;                 q += __shfl_xor(q, 1); q += __shfl_xor(q, 2);
;                 const float rstd = rsqrtf(q * (1.0f / 64.0f) + EPS);
; #pragma unroll
;                 for (int e = 0; e < 16; ++e) { const float y = xv[e] * rstd * lgv[e >> 2][e & 3] + lbv[e >> 2][e & 3]; VLT[(16 * qd + e) * VLP + jt] = (bf16_t)(pk2(y, 0.f) & 0xffffu); }
;             }
;             const int un = u + ustep;
.Lp3r_entry:
	s_and_b32 s10, s54, 31
	s_and_b32 s22, s10, 7
	s_lshr_b32 s11, s10, 3
	s_mul_i32 s12, s11, 5
	s_mul_i32 s13, s11, 11
	s_sub_u32 s13, s13, 12
	s_cmp_lt_u32 s11, 2
	s_cselect_b32 s12, s12, s13
	s_cselect_b32 s18, 5, 11
	s_and_b32 s39, s39, 0xffffff00
	s_lshr_b32 s39, s39, 3
	s_add_u32 s21, s39, s12
	s_mul_i32 s24, s21, 0x60000
	s_lshl_b32 s25, s22, 7
	s_add_u32 s24, s24, s25
	s_add_u32 s24, s24, 0x6000000
	s_add_u32 s26, s8, s24
	s_addc_u32 s27, s9, 0
	s_lshl_b32 s24, s21, 18
	s_add_u32 s24, s24, s25
	s_add_u32 s24, s24, 0x14a00000
	s_add_u32 s48, s8, s24
	s_addc_u32 s49, s9, 0
	s_lshl_b32 s24, s22, 15
	s_add_u32 s24, s24, 0x180000
	s_add_u32 s36, s8, s24
	s_addc_u32 s37, s9, 0
	s_lshl_b32 s24, s22, 9
	s_add_u32 s46, s16, s24
	s_addc_u32 s47, s17, 0
	s_lshl_b32 s24, s22, 8
	s_add_u32 s50, s40, s24
	s_addc_u32 s51, s41, 0
	s_add_u32 s52, s42, s24
	s_addc_u32 s53, s43, 0
	v_lshlrev_b32_e32 v109, 6, v104
	global_load_dwordx4 v[120:123], v114, s[36:37]
	global_load_dwordx4 v[124:127], v114, s[36:37] offset:32
	global_load_dwordx4 v[128:131], v114, s[36:37] offset:64
	global_load_dwordx4 v[132:135], v114, s[36:37] offset:96
	global_load_dwordx4 v[136:139], v114, s[36:37] offset:128
	global_load_dwordx4 v[140:143], v114, s[36:37] offset:160
	global_load_dwordx4 v[144:147], v114, s[36:37] offset:192
	global_load_dwordx4 v[148:151], v114, s[36:37] offset:224
	global_load_dword v32, v115, s[46:47]
	global_load_dwordx4 v[152:155], v109, s[50:51]
	global_load_dwordx4 v[156:159], v109, s[50:51] offset:16
	global_load_dwordx4 v[160:163], v109, s[50:51] offset:32
	global_load_dwordx4 v[164:167], v109, s[50:51] offset:48
	global_load_dwordx4 v[168:171], v109, s[52:53]
	global_load_dwordx4 v[172:175], v109, s[52:53] offset:16
	global_load_dwordx4 v[176:179], v109, s[52:53] offset:32
	global_load_dwordx4 v[180:183], v109, s[52:53] offset:48
	s_mov_b32 s45, 0
	global_load_dwordx4 v[16:19], v112, s[26:27]
	global_load_dwordx4 v[20:23], v112, s[26:27] offset:16
	global_load_dwordx2 v[24:25], v113, s[26:27]
	global_load_dwordx2 v[26:27], v113, s[26:27] offset:16
	global_load_dwordx2 v[28:29], v113, s[26:27] offset:32
	global_load_dwordx2 v[30:31], v113, s[26:27] offset:48
	s_add_u32 s26, s26, 0x60000
	s_addc_u32 s27, s27, 0
	s_cmp_lt_u32 s18, 2
	s_cbranch_scc1 .Lp3r_tail0
	global_load_dwordx4 v[40:43], v112, s[26:27]
	global_load_dwordx4 v[44:47], v112, s[26:27] offset:16
	global_load_dwordx2 v[48:49], v113, s[26:27]
	global_load_dwordx2 v[50:51], v113, s[26:27] offset:16
	global_load_dwordx2 v[52:53], v113, s[26:27] offset:32
	global_load_dwordx2 v[54:55], v113, s[26:27] offset:48
	s_add_u32 s26, s26, 0x60000
	s_addc_u32 s27, s27, 0
